# sample-row mini-GEMMs: the operand shared by all 8 waves is now loaded once per workgroup (one fragment per wave) and broadcast through double-buffered LDS instead of 8x redundant global gathers
# speedup vs baseline: 1.0668x; 1.0267x over previous
; __device__ __forceinline__ int tidx() { int t = (int)__builtin_amdgcn_workitem_id_x(); asm volatile("" : "+v"(t)); return t; }
; __device__ __forceinline__ unsigned cvt_pk_bf16(float lo, float hi) { unsigned r; asm("v_cvt_pk_bf16_f32 %0, %1, %2" : "=v"(r) : "v"(lo), "v"(hi)); return r; }
; __device__ __forceinline__ float sigm(float x) { return rcpf_(1.f + __expf(-x)); }
; __device__ __forceinline__ float lo_bf(unsigned w) { return __uint_as_float(w << 16); }
; __device__ __forceinline__ f32x4 mini_tile(const bf16_t* __restrict__ A, const bf16_t* __restrict__ Bt, int K, int m0, int n0, int lane) {
;     const bf16_t* ap = A + (size_t)(m0 + (lane & 15)) * K + 8 * (lane >> 4);
;     const bf16_t* bp = Bt + (size_t)(n0 + (lane & 15)) * K + 8 * (lane >> 4);
;     f32x4 acc0 = (f32x4){0.f, 0.f, 0.f, 0.f}, acc1 = (f32x4){0.f, 0.f, 0.f, 0.f};
; #pragma unroll 1
;     for (int k0 = 0; k0 < K; k0 += 256) {
;         bf16x8 a[8], b[8];
; #pragma unroll
;         for (int i = 0; i < 8; ++i) { a[i] = *(const bf16x8*)(ap + k0 + 32 * i); b[i] = *(const bf16x8*)(bp + k0 + 32 * i); }
; #pragma unroll
;         for (int i = 0; i < 8; i += 2) { acc0 = __builtin_amdgcn_mfma_f32_16x16x32_bf16(b[i], a[i], acc0, 0, 0, 0); acc1 = __builtin_amdgcn_mfma_f32_16x16x32_bf16(b[i + 1], a[i + 1], acc1, 0, 0, 0); }
;     }
;     return acc0 + acc1;
; }
; __device__ __forceinline__ void mini_branch(const Params& p, int l, int bid, int nblk) {
;     const int tid = tidx(), wid = tid >> 6, lane = tid & 63, g = lane >> 4;
;     for (int s = bid; s < 256; s += nblk) {
;         const int m0 = SEQ + 16 * (s >> 3), n0 = 128 * (s & 7) + 16 * wid, m = m0 + (lane & 15), n = n0 + 4 * g;
;         f32x4 val = (f32x4){0.f, 0.f, 0.f, 0.f};
; #pragma unroll 1
;         for (int z = 0; z < 3; ++z) {
;             const f32x4 acc = mini_tile(p.Y + (size_t)z * MROWS * 1024, p.WbrT + (size_t)(l * 3 + z) * 1048576, 1024, m0, n0, lane);
;             const u32x2 gw = *(const u32x2*)(p.P + (size_t)m * NIN + C_GM + z * 1024 + n);
;             val[0] += sigm(lo_bf(gw.x)) * acc[0]; val[1] += sigm(hi_bf(gw.x)) * acc[1]; val[2] += sigm(lo_bf(gw.y)) * acc[2]; val[3] += sigm(hi_bf(gw.y)) * acc[3];
;         }
;         u32x2 w; w.x = cvt_pk_bf16(val[0], val[1]); w.y = cvt_pk_bf16(val[2], val[3]);
;         *(u32x2*)(p.merged + (size_t)m * 1024 + n) = w;
.LBB0_220:
	s_movk_i32 s16, 0xff00
	v_mov_b64_e32 v[24:25], v[14:15]
	v_mov_b64_e32 v[26:27], v[10:11]
	v_mov_b32_e32 v0, 0
	v_mov_b32_e32 v1, v32
	v_mov_b32_e32 v2, v32
	v_mov_b32_e32 v3, v32
	s_waitcnt vmcnt(0)
	v_mov_b32_e32 v6, 0
	v_mov_b32_e32 v7, v32
	v_mov_b32_e32 v8, v32
	v_mov_b32_e32 v9, v32
	v_and_b32_e32 v104, 0x1c0, v234
	v_mov_b32_e32 v105, 0
	v_lshlrev_b32_e32 v110, 4, v234
	v_and_b32_e32 v111, 63, v234
	v_lshlrev_b32_e32 v111, 4, v111
.LBB0_221:
	v_lshl_add_u64 v[68:69], v[26:27], 0, v[4:5]
	v_lshl_add_u64 v[66:67], v[24:25], 0, v[4:5]
	v_lshl_add_u64 v[102:103], v[104:105], 0, v[66:67]
	global_load_dwordx4 v[106:109], v[102:103], off
	global_load_dwordx4 v[34:37], v[68:69], off
	global_load_dwordx4 v[38:41], v[68:69], off offset:64
	global_load_dwordx4 v[50:53], v[68:69], off offset:128
	global_load_dwordx4 v[58:61], v[68:69], off offset:192
	global_load_dwordx4 v[70:73], v[68:69], off offset:256
	global_load_dwordx4 v[78:81], v[68:69], off offset:320
	global_load_dwordx4 v[86:89], v[68:69], off offset:384
	global_load_dwordx4 v[94:97], v[68:69], off offset:448
	s_addk_i32 s16, 0x100
	v_lshl_add_u64 v[26:27], v[26:27], 0, s[54:55]
	s_cmpk_lt_u32 s16, 0x300
	v_lshl_add_u64 v[24:25], v[24:25], 0, s[54:55]
	s_waitcnt vmcnt(8)
	ds_write_b128 v110, v[106:109]
	s_waitcnt lgkmcnt(0)
	s_barrier
	ds_read_b128 v[42:45], v111
	ds_read_b128 v[46:49], v111 offset:1024
	ds_read_b128 v[54:57], v111 offset:2048
	ds_read_b128 v[62:65], v111 offset:3072
	ds_read_b128 v[74:77], v111 offset:4096
	ds_read_b128 v[82:85], v111 offset:5120
	ds_read_b128 v[90:93], v111 offset:6144
	ds_read_b128 v[98:101], v111 offset:7168
	v_xor_b32_e32 v110, 0x2000, v110
	v_xor_b32_e32 v111, 0x2000, v111
	s_waitcnt vmcnt(7) lgkmcnt(7)
	v_mfma_f32_16x16x32_bf16 v[0:3], v[34:37], v[42:45], v[0:3]
	s_waitcnt vmcnt(6) lgkmcnt(6)
	v_mfma_f32_16x16x32_bf16 v[6:9], v[38:41], v[46:49], v[6:9]
	s_waitcnt vmcnt(5) lgkmcnt(5)
	v_mfma_f32_16x16x32_bf16 v[0:3], v[50:53], v[54:57], v[0:3]
	s_waitcnt vmcnt(4) lgkmcnt(4)
	v_mfma_f32_16x16x32_bf16 v[6:9], v[58:61], v[62:65], v[6:9]
	s_waitcnt vmcnt(3) lgkmcnt(3)
	v_mfma_f32_16x16x32_bf16 v[0:3], v[70:73], v[74:77], v[0:3]
	s_waitcnt vmcnt(2) lgkmcnt(2)
	v_mfma_f32_16x16x32_bf16 v[6:9], v[78:81], v[82:85], v[6:9]
	s_waitcnt vmcnt(1) lgkmcnt(1)
	v_mfma_f32_16x16x32_bf16 v[0:3], v[86:89], v[90:93], v[0:3]
	s_waitcnt vmcnt(0) lgkmcnt(0)
	v_mfma_f32_16x16x32_bf16 v[6:9], v[94:97], v[98:101], v[6:9]
	s_cbranch_scc1 .LBB0_221
	s_lshl_b32 s50, s9, 11
	v_lshl_add_u64 v[24:25], v[18:19], 0, s[50:51]
	global_load_dwordx2 v[24:25], v[24:25], off
	s_nop 3
	v_pk_add_f32 v[2:3], v[2:3], v[8:9]
	v_pk_add_f32 v[0:1], v[0:1], v[6:7]
	s_add_i32 s9, s9, 1
	s_mov_b64 s[16:17], 0x200000
	v_lshl_add_u64 v[10:11], v[10:11], 0, s[16:17]
	s_cmp_eq_u32 s9, 3
	v_lshl_add_u64 v[14:15], v[14:15], 0, s[60:61]
	s_waitcnt vmcnt(0)
	v_lshlrev_b32_e32 v6, 16, v24
	v_and_b32_e32 v7, 0xffff0000, v24
	v_lshlrev_b32_e32 v8, 16, v25
	v_and_b32_e32 v9, 0xffff0000, v25
	v_mul_f32_e32 v6, 0xbfb8aa3b, v6
	v_mul_f32_e32 v7, 0xbfb8aa3b, v7
	v_mul_f32_e32 v8, 0xbfb8aa3b, v8
	v_mul_f32_e32 v9, 0xbfb8aa3b, v9
	v_exp_f32_e32 v6, v6
	v_exp_f32_e32 v7, v7
	v_exp_f32_e32 v8, v8
	v_exp_f32_e32 v9, v9
	v_add_f32_e32 v6, 1.0, v6
	v_add_f32_e32 v7, 1.0, v7
	v_add_f32_e32 v8, 1.0, v8
	v_add_f32_e32 v9, 1.0, v9
	v_rcp_f32_e32 v6, v6
	v_rcp_f32_e32 v7, v7
	v_rcp_f32_e32 v8, v8
	v_rcp_f32_e32 v9, v9
	v_pk_fma_f32 v[22:23], v[0:1], v[6:7], v[22:23]
	v_pk_fma_f32 v[20:21], v[2:3], v[8:9], v[20:21]
	s_cbranch_scc0 .LBB0_220
	v_lshlrev_b64 v[0:1], 11, v[16:17]
	v_lshl_add_u64 v[0:1], s[18:19], 0, v[0:1]
	s_add_i32 s8, s8, s42
	s_add_i32 s4, s4, s5
	s_add_i32 s6, s6, s7
	v_lshl_add_u64 v[0:1], v[12:13], 1, v[0:1]
	s_cmpk_gt_i32 s8, 0xff
	v_cvt_pk_bf16_f32 v2, v22, v23
	v_cvt_pk_bf16_f32 v3, v20, v21
	global_store_dwordx2 v[0:1], v[2:3], off
	s_cbranch_scc0 .LBB0_219

; __device__ __forceinline__ f32x4 mini_tile(const bf16_t* __restrict__ A, const bf16_t* __restrict__ Bt, int K, int m0, int n0, int lane) {
;     const bf16_t* ap = A + (size_t)(m0 + (lane & 15)) * K + 8 * (lane >> 4);
;     const bf16_t* bp = Bt + (size_t)(n0 + (lane & 15)) * K + 8 * (lane >> 4);
;     f32x4 acc0 = (f32x4){0.f, 0.f, 0.f, 0.f}, acc1 = (f32x4){0.f, 0.f, 0.f, 0.f};
; #pragma unroll 1
;     for (int k0 = 0; k0 < K; k0 += 256) {
;         bf16x8 a[8], b[8];
; #pragma unroll
;         for (int i = 0; i < 8; ++i) { a[i] = *(const bf16x8*)(ap + k0 + 32 * i); b[i] = *(const bf16x8*)(bp + k0 + 32 * i); }
; #pragma unroll
;         for (int i = 0; i < 8; i += 2) { acc0 = __builtin_amdgcn_mfma_f32_16x16x32_bf16(b[i], a[i], acc0, 0, 0, 0); acc1 = __builtin_amdgcn_mfma_f32_16x16x32_bf16(b[i + 1], a[i + 1], acc1, 0, 0, 0); }
;     }
;     return acc0 + acc1;
; }
; __device__ __forceinline__ void mini_branch(const Params& p, int l, int bid, int nblk) {
;     const int tid = tidx(), wid = tid >> 6, lane = tid & 63, g = lane >> 4;
;     for (int s = bid; s < 256; s += nblk) {
;         const int m0 = SEQ + 16 * (s >> 3), n0 = 128 * (s & 7) + 16 * wid, m = m0 + (lane & 15), n = n0 + 4 * g;
;         f32x4 val = (f32x4){0.f, 0.f, 0.f, 0.f};
; #pragma unroll 1
;         for (int z = 0; z < 3; ++z) {
;             const f32x4 acc = mini_tile(p.Y + (size_t)z * MROWS * 1024, p.WbrT + (size_t)(l * 3 + z) * 1048576, 1024, m0, n0, lane);
;             const u32x2 gw = *(const u32x2*)(p.P + (size_t)m * NIN + C_GM + z * 1024 + n);
;             val[0] += sigm(lo_bf(gw.x)) * acc[0]; val[1] += sigm(hi_bf(gw.x)) * acc[1]; val[2] += sigm(lo_bf(gw.y)) * acc[2]; val[3] += sigm(hi_bf(gw.y)) * acc[3];
;         }
;         u32x2 w; w.x = cvt_pk_bf16(val[0], val[1]); w.y = cvt_pk_bf16(val[2], val[3]);
;         *(u32x2*)(p.merged + (size_t)m * 1024 + n) = w;
;     }
; }
; __device__ __forceinline__ void mini_res(const float* Xin, float* Xo, bf16_t* Xbo, const bf16_t* A, const bf16_t* Bt, int K, float* sumsq, int bid, int nblk) {
;     const int tid = tidx(), wid = tid >> 6, lane = tid & 63, g = lane >> 4;
;     for (int s = bid; s < 256; s += nblk) {
;         const int m0 = SEQ + 16 * (s >> 3), n0 = 128 * (s & 7) + 16 * wid, m = m0 + (lane & 15), n = n0 + 4 * g;
;         const f32x4 acc = mini_tile(A, Bt, K, m0, n0, lane);
;         float* xp = Xo + (size_t)m * 1024 + n;
.LBB0_801:
	s_and_b32 s4, s9, 0x380
	v_add_u32_e32 v2, s4, v17
	s_waitcnt lgkmcnt(0)
	v_mov_b64_e32 v[0:1], s[14:15]
	v_mad_i64_i32 v[10:11], s[4:5], s8, v2, v[0:1]
	s_and_b32 s4, s11, -16
	s_nop 0
	v_add_u32_e32 v2, s4, v16
	v_mov_b64_e32 v[0:1], s[20:21]
	v_mad_i64_i32 v[12:13], s[4:5], s8, v2, v[0:1]
	v_mov_b32_e32 v0, 0
	s_mov_b32 s4, 0
	v_mov_b32_e32 v1, v0
	v_mov_b32_e32 v2, v0
	v_mov_b32_e32 v3, v0
	s_waitcnt vmcnt(8)
	v_mov_b32_e32 v6, v0
	v_mov_b32_e32 v7, v0
	v_mov_b32_e32 v8, v0
	v_mov_b32_e32 v9, v0
	v_and_b32_e32 v88, 0x1c0, v234
	v_mov_b32_e32 v89, 0
	v_lshlrev_b32_e32 v94, 4, v234
	v_and_b32_e32 v95, 63, v234
	v_lshlrev_b32_e32 v95, 4, v95
.LBB0_802:
	v_lshl_add_u64 v[48:49], v[10:11], 0, v[4:5]
	v_lshl_add_u64 v[46:47], v[12:13], 0, v[4:5]
	v_lshl_add_u64 v[86:87], v[88:89], 0, v[46:47]
	global_load_dwordx4 v[90:93], v[86:87], off
	global_load_dwordx4 v[18:21], v[48:49], off
	global_load_dwordx4 v[26:29], v[48:49], off offset:64
	global_load_dwordx4 v[34:37], v[48:49], off offset:128
	global_load_dwordx4 v[42:45], v[48:49], off offset:192
	global_load_dwordx4 v[54:57], v[48:49], off offset:256
	global_load_dwordx4 v[62:65], v[48:49], off offset:320
	global_load_dwordx4 v[70:73], v[48:49], off offset:384
	global_load_dwordx4 v[78:81], v[48:49], off offset:448
	s_addk_i32 s4, 0x100
	v_lshl_add_u64 v[10:11], v[10:11], 0, s[54:55]
	s_cmp_lt_u32 s4, s49
	v_lshl_add_u64 v[12:13], v[12:13], 0, s[54:55]
	s_waitcnt vmcnt(8)
	ds_write_b128 v94, v[90:93]
	s_waitcnt lgkmcnt(0)
	s_barrier
	ds_read_b128 v[22:25], v95
	ds_read_b128 v[30:33], v95 offset:1024
	ds_read_b128 v[38:41], v95 offset:2048
	ds_read_b128 v[50:53], v95 offset:3072
	ds_read_b128 v[58:61], v95 offset:4096
	ds_read_b128 v[66:69], v95 offset:5120
	ds_read_b128 v[74:77], v95 offset:6144
	ds_read_b128 v[82:85], v95 offset:7168
	v_xor_b32_e32 v94, 0x2000, v94
	v_xor_b32_e32 v95, 0x2000, v95
	s_waitcnt vmcnt(7) lgkmcnt(7)
	v_mfma_f32_16x16x32_bf16 v[0:3], v[18:21], v[22:25], v[0:3]
	s_waitcnt vmcnt(6) lgkmcnt(6)
	v_mfma_f32_16x16x32_bf16 v[6:9], v[26:29], v[30:33], v[6:9]
	s_waitcnt vmcnt(5) lgkmcnt(5)
	v_mfma_f32_16x16x32_bf16 v[0:3], v[34:37], v[38:41], v[0:3]
	s_waitcnt vmcnt(4) lgkmcnt(4)
	v_mfma_f32_16x16x32_bf16 v[6:9], v[42:45], v[50:53], v[6:9]
	s_waitcnt vmcnt(3) lgkmcnt(3)
	v_mfma_f32_16x16x32_bf16 v[0:3], v[54:57], v[58:61], v[0:3]
	s_waitcnt vmcnt(2) lgkmcnt(2)
	v_mfma_f32_16x16x32_bf16 v[6:9], v[62:65], v[66:69], v[6:9]
	s_waitcnt vmcnt(1) lgkmcnt(1)
	v_mfma_f32_16x16x32_bf16 v[0:3], v[70:73], v[74:77], v[0:3]
	s_waitcnt vmcnt(0) lgkmcnt(0)
	v_mfma_f32_16x16x32_bf16 v[6:9], v[78:81], v[82:85], v[6:9]
	s_cbranch_scc1 .LBB0_802
	s_lshl_b32 s4, s13, 1
	s_lshl_b32 s5, s13, 7
	s_and_b32 s4, s4, -16
	s_and_b32 s5, s5, 0x380
	v_add_u32_e32 v12, s5, v14
	v_add_u32_e32 v10, s4, v16
	v_ashrrev_i32_e32 v11, 31, v10
	v_or_b32_e32 v12, v12, v15
	v_pk_add_f32 v[6:7], v[0:1], v[6:7]
	v_lshlrev_b64 v[0:1], 12, v[10:11]
	v_ashrrev_i32_e32 v13, 31, v12
	v_pk_add_f32 v[8:9], v[2:3], v[8:9]
	v_lshl_add_u64 v[2:3], s[16:17], 0, v[0:1]
	v_lshlrev_b64 v[18:19], 2, v[12:13]
	v_lshl_add_u64 v[0:1], s[6:7], 0, v[0:1]
	v_lshl_add_u64 v[0:1], v[0:1], 0, v[18:19]
	v_lshl_add_u64 v[20:21], v[2:3], 0, v[18:19]
	global_load_dwordx4 v[0:3], v[0:1], off
	s_waitcnt vmcnt(0)
	v_pk_add_f32 v[2:3], v[8:9], v[2:3]
	v_pk_add_f32 v[0:1], v[6:7], v[0:1]
	global_store_dwordx4 v[20:21], v[0:3], off
	v_cvt_pk_bf16_f32 v6, v0, v1
	v_cvt_pk_bf16_f32 v7, v2, v3
	v_lshlrev_b64 v[8:9], 11, v[10:11]
	v_lshl_add_u64 v[8:9], s[18:19], 0, v[8:9]
	v_mul_f32_e32 v1, v1, v1
	v_fmac_f32_e32 v1, v0, v0
	v_mul_f32_e32 v0, v3, v3
	v_fmac_f32_e32 v0, v2, v2
	v_and_b32_e32 v2, 64, v240
	v_add_f32_e32 v0, v1, v0
	v_xor_b32_e32 v1, 16, v240
	v_add_u32_e32 v2, 64, v2
	v_cmp_lt_i32_e64 s[4:5], v1, v2
	v_lshl_add_u64 v[8:9], v[12:13], 1, v[8:9]
	global_store_dwordx2 v[8:9], v[6:7], off
	v_cndmask_b32_e64 v1, v240, v1, s[4:5]
	v_lshlrev_b32_e32 v1, 2, v1
	ds_bpermute_b32 v1, v1, v0
	s_waitcnt lgkmcnt(0)
	v_add_f32_e32 v0, v0, v1
	v_xor_b32_e32 v1, 32, v240
	v_cmp_lt_i32_e64 s[4:5], v1, v2
	s_nop 1
	v_cndmask_b32_e64 v1, v240, v1, s[4:5]
	v_lshlrev_b32_e32 v1, 2, v1
	ds_bpermute_b32 v1, v1, v0
	s_and_saveexec_b64 s[4:5], vcc
	s_cbranch_execz .LBB0_800
	s_waitcnt lgkmcnt(0)
	v_add_f32_e32 v2, v0, v1
	v_lshl_add_u64 v[0:1], v[10:11], 2, s[22:23]
	global_atomic_add_f32 v[0:1], v2, off
	s_branch .LBB0_800
